# sample-row GEMM of P3/P8: all sixteen operand loads issued up front with counted waits (paired re-test on the current base)
# baseline (speedup 1.0000x reference)
.LBB0_769:
	s_or_b64 exec, exec, s[42:43]
	v_add_u32_e32 v10, s22, v17
	v_ashrrev_i32_e32 v11, 31, v10
	v_or_b32_e32 v18, s21, v12
	v_lshlrev_b64 v[10:11], 11, v[10:11]
	v_ashrrev_i32_e32 v19, 31, v18
	v_lshl_add_u64 v[10:11], v[2:3], 0, v[10:11]
	v_lshlrev_b64 v[18:19], 11, v[18:19]
	v_add_co_u32_e32 v48, vcc, 0x8000, v10
	v_lshl_add_u64 v[46:47], v[4:5], 0, v[18:19]
	s_nop 0
	v_addc_co_u32_e32 v49, vcc, 0, v11, vcc
	v_add_co_u32_e32 v50, vcc, 0x8000, v46
	v_addc_co_u32_e32 v51, vcc, 0, v47, vcc
	global_load_dwordx4 v[52:55], v[46:47], off
	global_load_dwordx4 v[68:71], v[10:11], off
	global_load_dwordx4 v[84:87], v[50:51], off
	global_load_dwordx4 v[100:103], v[48:49], off
	global_load_dwordx4 v[56:59], v[46:47], off offset:64
	global_load_dwordx4 v[72:75], v[10:11], off offset:64
	global_load_dwordx4 v[88:91], v[50:51], off offset:64
	global_load_dwordx4 v[104:107], v[48:49], off offset:64
	global_load_dwordx4 v[60:63], v[46:47], off offset:128
	global_load_dwordx4 v[76:79], v[10:11], off offset:128
	global_load_dwordx4 v[92:95], v[50:51], off offset:128
	global_load_dwordx4 v[108:111], v[48:49], off offset:128
	global_load_dwordx4 v[64:67], v[46:47], off offset:192
	global_load_dwordx4 v[80:83], v[10:11], off offset:192
	global_load_dwordx4 v[96:99], v[50:51], off offset:192
	global_load_dwordx4 v[112:115], v[48:49], off offset:192
	v_add_u32_e32 v10, s19, v13
	s_waitcnt vmcnt(12)
	v_mfma_f32_16x16x32_bf16 v[30:33], v[52:55], v[68:71], 0
	v_mfma_f32_16x16x32_bf16 v[18:21], v[52:55], v[100:103], 0
	v_mfma_f32_16x16x32_bf16 v[22:25], v[84:87], v[68:71], 0
	v_mfma_f32_16x16x32_bf16 v[26:29], v[84:87], v[100:103], 0
	s_waitcnt vmcnt(8)
	v_mfma_f32_16x16x32_bf16 v[30:33], v[56:59], v[72:75], v[30:33]
	v_mfma_f32_16x16x32_bf16 v[18:21], v[56:59], v[104:107], v[18:21]
	v_mfma_f32_16x16x32_bf16 v[22:25], v[88:91], v[72:75], v[22:25]
	v_mfma_f32_16x16x32_bf16 v[26:29], v[88:91], v[104:107], v[26:29]
	s_waitcnt vmcnt(4)
	v_mfma_f32_16x16x32_bf16 v[30:33], v[60:63], v[76:79], v[30:33]
	v_mfma_f32_16x16x32_bf16 v[18:21], v[60:63], v[108:111], v[18:21]
	v_mfma_f32_16x16x32_bf16 v[22:25], v[92:95], v[76:79], v[22:25]
	v_mfma_f32_16x16x32_bf16 v[26:29], v[92:95], v[108:111], v[26:29]
	s_waitcnt vmcnt(0)
	v_mfma_f32_16x16x32_bf16 v[30:33], v[64:67], v[80:83], v[30:33]
	v_mfma_f32_16x16x32_bf16 v[18:21], v[64:67], v[112:115], v[18:21]
	v_mfma_f32_16x16x32_bf16 v[22:25], v[96:99], v[80:83], v[22:25]
	v_mfma_f32_16x16x32_bf16 v[26:29], v[96:99], v[112:115], v[26:29]
	s_nop 7
	s_nop 1
	ds_write_b128 v10, v[30:33]
	s_nop 0
	ds_write_b128 v10, v[18:21] offset:2048
	s_nop 1
	ds_write_b128 v10, v[22:25] offset:1024
	ds_write_b128 v10, v[26:29] offset:3072
	s_waitcnt lgkmcnt(0)
	s_barrier
	s_and_saveexec_b64 s[42:43], s[0:1]
	s_cbranch_execz .LBB0_766
	v_lshlrev_b32_e32 v22, 16, v8
	v_and_b32_e32 v23, 0xffff0000, v8
	v_lshlrev_b32_e32 v24, 16, v9
	v_and_b32_e32 v25, 0xffff0000, v9
	ds_read_b128 v[8:11], v14
	ds_read_b128 v[18:21], v15 offset:4096
	s_andn2_b64 vcc, exec, s[94:95]
	s_waitcnt lgkmcnt(0)
	v_pk_add_f32 v[20:21], v[10:11], v[20:21]
	v_pk_add_f32 v[18:19], v[8:9], v[18:19]
	ds_read_b128 v[8:11], v15 offset:8192
	s_waitcnt lgkmcnt(0)
	v_pk_add_f32 v[20:21], v[20:21], v[10:11]
	v_pk_add_f32 v[18:19], v[18:19], v[8:9]
	ds_read_b128 v[8:11], v15 offset:12288
	s_waitcnt lgkmcnt(0)
	v_pk_add_f32 v[20:21], v[20:21], v[10:11]
	v_pk_add_f32 v[18:19], v[18:19], v[8:9]
	ds_read_b128 v[8:11], v15 offset:16384
	s_waitcnt lgkmcnt(0)
	v_pk_add_f32 v[20:21], v[20:21], v[10:11]
	v_pk_add_f32 v[18:19], v[18:19], v[8:9]
	ds_read_b128 v[8:11], v15 offset:20480
	s_waitcnt lgkmcnt(0)
	v_pk_add_f32 v[20:21], v[20:21], v[10:11]
	v_pk_add_f32 v[18:19], v[18:19], v[8:9]
	ds_read_b128 v[8:11], v15 offset:24576
	s_waitcnt lgkmcnt(0)
	v_pk_add_f32 v[20:21], v[20:21], v[10:11]
	v_pk_add_f32 v[18:19], v[18:19], v[8:9]
	ds_read_b128 v[8:11], v15 offset:28672
	s_waitcnt lgkmcnt(0)
	v_pk_add_f32 v[10:11], v[20:21], v[10:11]
	v_pk_add_f32 v[18:19], v[18:19], v[8:9]
	v_pk_add_f32 v[8:9], v[10:11], v[24:25]
	v_pk_add_f32 v[10:11], v[18:19], v[22:23]
	s_cbranch_vccnz .LBB0_772
	v_lshlrev_b64 v[18:19], 11, v[6:7]
	v_add_u32_e32 v20, s21, v0
	v_ashrrev_i32_e32 v21, 31, v20
	v_lshl_add_u64 v[18:19], s[64:65], 0, v[18:19]
	v_lshl_add_u64 v[18:19], v[20:21], 1, v[18:19]
	v_cvt_pk_bf16_f32 v20, v10, v11
	v_cvt_pk_bf16_f32 v21, v8, v9
	global_store_dwordx2 v[18:19], v[20:21], off
